# scan_b chunk-to-workgroup map aligned with the XCD panel ownership; barrier after it becomes XCD-group-local
# baseline (speedup 1.0000x reference)
.LBB0_936:
	s_cmp_lt_i32 s78, 8
	s_cselect_b64 s[4:5], -1, 0
	s_cmp_gt_i32 s79, 7
	s_cselect_b64 s[0:1], -1, 0
	s_and_b64 s[0:1], s[4:5], s[0:1]
	s_andn2_b64 vcc, exec, s[0:1]
	s_cbranch_vccnz .LBB0_952
	s_movk_i32 s0, 0x100
	v_cmp_gt_u32_e32 vcc, s0, v185
	s_and_saveexec_b64 s[6:7], vcc
	s_cbranch_execz .LBB0_951
	s_and_b32 s0, s2, 7
	s_lshl_b32 s0, s0, 5
	s_lshr_b32 s3, s2, 3
	s_add_u32 s0, s0, s3
	v_lshl_or_b32 v12, s0, 8, v185
	s_mov_b32 s0, 0x10000
	v_cmp_gt_i32_e32 vcc, s0, v12
	s_and_b64 exec, exec, vcc
	s_cbranch_execz .LBB0_951
	s_add_u32 s8, s76, 0x100000
	s_addc_u32 s9, s77, 0
	v_mov_b32_e32 v0, 0
	s_add_u32 s10, s76, 0x200000
	v_lshlrev_b32_e32 v2, 3, v185
	v_mov_b32_e32 v3, v0
	s_addc_u32 s11, s77, 0
	s_lshl_b32 s3, s64, 8
	v_add_u32_e32 v13, 0x700, v185
	v_lshl_add_u64 v[6:7], s[76:77], 0, v[2:3]
	s_mov_b64 s[12:13], 0
	s_movk_i32 s14, 0xc000
	s_mov_b32 s15, 0x8500000
	s_mov_b32 s16, 0x6500000
	s_mov_b32 s17, 0xc500000
	s_mov_b32 s18, 0xa501000
	s_mov_b32 s19, 0x8501000
	s_mov_b32 s20, 0x6501000
	s_mov_b32 s21, 0xc501000
	s_mov_b32 s22, 0xa502000
	s_mov_b32 s23, 0x8502000
	s_mov_b32 s26, 0x6502000
	s_mov_b32 s27, 0xc502000
	s_mov_b32 s28, 0xa503000
	s_mov_b32 s29, 0x8503000
	s_mov_b32 s30, 0x6503000
	s_mov_b32 s31, 0xc503000
	s_mov_b32 s34, 0xffff

.LBB0_952:
	s_cmp_gt_i32 s79, 8
	s_cselect_b64 s[6:7], -1, 0
	s_and_b64 s[0:1], s[4:5], s[6:7]
	s_andn2_b64 vcc, exec, s[0:1]
	s_cbranch_vccnz .LBB0_1006
	s_waitcnt vmcnt(0) lgkmcnt(0)
	s_barrier
	v_readlane_b32 s12, v243, 0
	s_cmp_eq_u32 s12, 0
	s_cbranch_scc1 .Lfb_5
	v_readlane_b32 s21, v243, 1
	s_add_u32 s21, s21, 1
	v_writelane_b32 v243, s21, 1
	v_readlane_b32 s12, v242, 1
	v_readlane_b32 s13, v242, 2
	s_mov_b64 s[14:15], exec
	s_and_b64 s[12:13], s[14:15], s[12:13]
	s_mov_b64 exec, s[12:13]
	s_cbranch_execz .Llb_done_5
	s_and_b32 s16, s2, 7
	s_lshl_b32 s16, s16, 6
	s_add_u32 s16, s76, s16
	s_addc_u32 s17, s77, 0
	v_mov_b32_e32 v1, 0x3000
	v_mov_b32_e32 v4, 1
	global_atomic_add v1, v4, s[16:17] offset:2112
	buffer_inv sc1
	s_lshl_b32 s23, s21, 5

.Llb_after_5:
.LBB0_1006:
	s_cmp_lt_i32 s78, 9
	s_cselect_b64 s[0:1], -1, 0
	s_and_b64 s[4:5], s[0:1], s[6:7]
	s_andn2_b64 vcc, exec, s[4:5]
	s_cbranch_vccnz .LBB0_1051
	s_cmpk_lt_i32 s2, 0x100
	s_cselect_b64 s[4:5], -1, 0
	s_cmpk_gt_i32 s2, 0xff
	v_readfirstlane_b32 s8, v185
	s_cbranch_scc1 .LBB0_1013
	s_ashr_i32 s3, s2, 31
	s_lshr_b32 s3, s3, 29
	s_add_i32 s3, s2, s3
	s_and_b32 s6, s3, -8
	s_sub_i32 s9, s2, s6
	s_cmp_gt_i32 s9, -1
	s_cbranch_scc0 .LBB0_1010
	s_lshl_b32 s10, s9, 5
	s_cbranch_execz .LBB0_1011
	s_branch .LBB0_1012
